# MLA softmax: cross-lane max exchange (ds_bpermute) moved into the rare rescale path; ballot on per-lane max is equivalent
# speedup vs baseline: 1.0050x; 1.0050x over previous
.LBB0_1448:
	s_nop 10
	v_max3_f32 v96, v48, v49, v50
	v_max3_f32 v98, v32, v33, v34
	v_max3_f32 v96, v96, v51, v52
	v_max3_f32 v98, v98, v35, v36
	v_max3_f32 v96, v96, v53, v54
	v_max3_f32 v98, v98, v37, v38
	v_max3_f32 v96, v96, v55, v56
	v_max3_f32 v98, v98, v39, v40
	v_max3_f32 v96, v96, v57, v58
	v_max3_f32 v98, v98, v41, v42
	v_max3_f32 v96, v96, v59, v60
	v_max3_f32 v98, v98, v43, v44
	v_max3_f32 v96, v96, v61, v62
	v_max3_f32 v98, v98, v45, v46
	v_max3_f32 v96, v96, v98, v63
	v_max_f32_e32 v96, v96, v47
	v_cmp_lt_f32_e32 vcc, s20, v96
	s_cbranch_vccz .LBB0_1450
	ds_bpermute_b32 v98, v185, v96
	s_waitcnt lgkmcnt(0)
	v_max_f32_e32 v96, v96, v98
	v_max_f32_e32 v96, v96, v96
	v_max_f32_e32 v96, 0, v96
	v_exp_f32_e64 v98, -v96
	v_add_f32_e32 v148, v148, v96
	v_pk_add_f32 v[48:49], v[48:49], v[96:97] op_sel_hi:[1,0] neg_lo:[0,1] neg_hi:[0,1]
	v_pk_add_f32 v[32:33], v[32:33], v[96:97] op_sel_hi:[1,0] neg_lo:[0,1] neg_hi:[0,1]
	v_mul_f32_e32 v129, v129, v98
	v_pk_add_f32 v[50:51], v[50:51], v[96:97] op_sel_hi:[1,0] neg_lo:[0,1] neg_hi:[0,1]
	v_pk_add_f32 v[34:35], v[34:35], v[96:97] op_sel_hi:[1,0] neg_lo:[0,1] neg_hi:[0,1]
	v_pk_add_f32 v[52:53], v[52:53], v[96:97] op_sel_hi:[1,0] neg_lo:[0,1] neg_hi:[0,1]
	v_pk_add_f32 v[36:37], v[36:37], v[96:97] op_sel_hi:[1,0] neg_lo:[0,1] neg_hi:[0,1]
	v_pk_add_f32 v[54:55], v[54:55], v[96:97] op_sel_hi:[1,0] neg_lo:[0,1] neg_hi:[0,1]
	v_pk_add_f32 v[38:39], v[38:39], v[96:97] op_sel_hi:[1,0] neg_lo:[0,1] neg_hi:[0,1]
	v_pk_add_f32 v[56:57], v[56:57], v[96:97] op_sel_hi:[1,0] neg_lo:[0,1] neg_hi:[0,1]
	v_pk_add_f32 v[40:41], v[40:41], v[96:97] op_sel_hi:[1,0] neg_lo:[0,1] neg_hi:[0,1]
	v_pk_add_f32 v[58:59], v[58:59], v[96:97] op_sel_hi:[1,0] neg_lo:[0,1] neg_hi:[0,1]
	v_pk_add_f32 v[42:43], v[42:43], v[96:97] op_sel_hi:[1,0] neg_lo:[0,1] neg_hi:[0,1]
	v_pk_add_f32 v[60:61], v[60:61], v[96:97] op_sel_hi:[1,0] neg_lo:[0,1] neg_hi:[0,1]
	v_pk_add_f32 v[44:45], v[44:45], v[96:97] op_sel_hi:[1,0] neg_lo:[0,1] neg_hi:[0,1]
	v_pk_add_f32 v[62:63], v[62:63], v[96:97] op_sel_hi:[1,0] neg_lo:[0,1] neg_hi:[0,1]
	v_pk_add_f32 v[46:47], v[46:47], v[96:97] op_sel_hi:[1,0] neg_lo:[0,1] neg_hi:[0,1]
	v_pk_mul_f32 v[30:31], v[30:31], v[98:99] op_sel_hi:[1,0]
	v_pk_mul_f32 v[28:29], v[28:29], v[98:99] op_sel_hi:[1,0]
	v_pk_mul_f32 v[26:27], v[26:27], v[98:99] op_sel_hi:[1,0]
	v_pk_mul_f32 v[24:25], v[24:25], v[98:99] op_sel_hi:[1,0]
	v_pk_mul_f32 v[22:23], v[22:23], v[98:99] op_sel_hi:[1,0]
	v_pk_mul_f32 v[20:21], v[20:21], v[98:99] op_sel_hi:[1,0]
	v_pk_mul_f32 v[18:19], v[18:19], v[98:99] op_sel_hi:[1,0]
	v_pk_mul_f32 v[16:17], v[16:17], v[98:99] op_sel_hi:[1,0]
	v_pk_mul_f32 v[14:15], v[14:15], v[98:99] op_sel_hi:[1,0]
	v_pk_mul_f32 v[12:13], v[12:13], v[98:99] op_sel_hi:[1,0]
	v_pk_mul_f32 v[10:11], v[10:11], v[98:99] op_sel_hi:[1,0]
	v_pk_mul_f32 v[8:9], v[8:9], v[98:99] op_sel_hi:[1,0]
	v_pk_mul_f32 v[6:7], v[6:7], v[98:99] op_sel_hi:[1,0]
	v_pk_mul_f32 v[4:5], v[4:5], v[98:99] op_sel_hi:[1,0]
	v_pk_mul_f32 v[2:3], v[2:3], v[98:99] op_sel_hi:[1,0]
	v_pk_mul_f32 v[0:1], v[0:1], v[98:99] op_sel_hi:[1,0]
.LBB0_1450:
	v_exp_f32_e32 v48, v48
	v_exp_f32_e32 v49, v49
	v_exp_f32_e32 v50, v50
	v_exp_f32_e32 v51, v51
	v_exp_f32_e32 v52, v52
	v_exp_f32_e32 v53, v53
	v_exp_f32_e32 v54, v54
	v_exp_f32_e32 v55, v55
	v_exp_f32_e32 v56, v56
	v_exp_f32_e32 v57, v57
	v_exp_f32_e32 v58, v58
	v_exp_f32_e32 v59, v59
	v_exp_f32_e32 v60, v60
	v_exp_f32_e32 v61, v61
	v_exp_f32_e32 v62, v62
	v_exp_f32_e32 v63, v63
	v_exp_f32_e32 v32, v32
	v_exp_f32_e32 v33, v33
	v_exp_f32_e32 v34, v34
	v_exp_f32_e32 v35, v35
	v_exp_f32_e32 v36, v36
	v_exp_f32_e32 v37, v37
	v_exp_f32_e32 v38, v38
	v_exp_f32_e32 v39, v39
	v_exp_f32_e32 v40, v40
	v_exp_f32_e32 v41, v41
	v_exp_f32_e32 v42, v42
	v_exp_f32_e32 v43, v43
	v_exp_f32_e32 v44, v44
	v_exp_f32_e32 v45, v45
	v_exp_f32_e32 v46, v46
	v_exp_f32_e32 v47, v47
	v_add_f32_e32 v149, v48, v49
	v_add_f32_e32 v150, v56, v57
	v_add_f32_e32 v151, v32, v33
	v_add_f32_e32 v152, v40, v41
	v_add_f32_e32 v149, v149, v50
	v_add_f32_e32 v150, v150, v58
	v_add_f32_e32 v151, v151, v34
	v_add_f32_e32 v152, v152, v42
	v_add_f32_e32 v149, v149, v51
	v_add_f32_e32 v150, v150, v59
	v_add_f32_e32 v151, v151, v35
	v_add_f32_e32 v152, v152, v43
	v_add_f32_e32 v149, v149, v52
	v_add_f32_e32 v150, v150, v60
	v_add_f32_e32 v151, v151, v36
	v_add_f32_e32 v152, v152, v44
	v_add_f32_e32 v149, v149, v53
	v_add_f32_e32 v150, v150, v61
	v_add_f32_e32 v151, v151, v37
	v_add_f32_e32 v152, v152, v45
	v_add_f32_e32 v149, v149, v54
	v_add_f32_e32 v150, v150, v62
	v_add_f32_e32 v151, v151, v38
	v_add_f32_e32 v152, v152, v46
	v_add_f32_e32 v149, v149, v55
	v_add_f32_e32 v150, v150, v63
	v_add_f32_e32 v151, v151, v39
	v_add_f32_e32 v152, v152, v47
	v_cvt_pk_bf16_f32 v236, v48, v49
	v_cvt_pk_bf16_f32 v237, v50, v51
	v_cvt_pk_bf16_f32 v238, v52, v53
	v_cvt_pk_bf16_f32 v239, v54, v55
	v_cvt_pk_bf16_f32 v240, v56, v57
	v_cvt_pk_bf16_f32 v241, v58, v59
	v_cvt_pk_bf16_f32 v242, v60, v61
	v_cvt_pk_bf16_f32 v243, v62, v63
	v_cvt_pk_bf16_f32 v244, v32, v33
	v_cvt_pk_bf16_f32 v245, v34, v35
	v_cvt_pk_bf16_f32 v246, v36, v37
	v_cvt_pk_bf16_f32 v247, v38, v39
	v_cvt_pk_bf16_f32 v186, v40, v41
	v_cvt_pk_bf16_f32 v187, v42, v43
	v_cvt_pk_bf16_f32 v188, v44, v45
	v_cvt_pk_bf16_f32 v189, v46, v47
	v_add_f32_e32 v149, v149, v150
	v_add_f32_e32 v151, v151, v152
	v_add_f32_e32 v149, v149, v151
	v_add_f32_e32 v129, v129, v149
	s_waitcnt lgkmcnt(0)
	v_mfma_f32_32x32x16_bf16 v[16:31], v[192:195], v[236:239], v[16:31]
	v_mfma_f32_32x32x16_bf16 v[0:15], v[196:199], v[236:239], v[0:15]
	v_mfma_f32_32x32x16_bf16 v[16:31], v[200:203], v[240:243], v[16:31]
	v_mfma_f32_32x32x16_bf16 v[0:15], v[204:207], v[240:243], v[0:15]
	v_mfma_f32_32x32x16_bf16 v[16:31], v[208:211], v[244:247], v[16:31]
	v_mfma_f32_32x32x16_bf16 v[0:15], v[212:215], v[244:247], v[0:15]
	v_mfma_f32_32x32x16_bf16 v[16:31], v[216:219], v[186:189], v[16:31]
	v_mfma_f32_32x32x16_bf16 v[0:15], v[162:165], v[186:189], v[0:15]

.LBB0_1470:
	v_exp_f32_e32 v48, v48
	v_exp_f32_e32 v49, v49
	v_exp_f32_e32 v50, v50
	v_exp_f32_e32 v51, v51
	v_exp_f32_e32 v52, v52
	v_exp_f32_e32 v53, v53
	v_exp_f32_e32 v54, v54
	v_exp_f32_e32 v55, v55
	v_exp_f32_e32 v56, v56
	v_exp_f32_e32 v57, v57
	v_exp_f32_e32 v58, v58
	v_exp_f32_e32 v59, v59
	v_exp_f32_e32 v60, v60
	v_exp_f32_e32 v61, v61
	v_exp_f32_e32 v62, v62
	v_exp_f32_e32 v63, v63
	v_exp_f32_e32 v32, v32
	v_exp_f32_e32 v33, v33
	v_exp_f32_e32 v34, v34
	v_exp_f32_e32 v35, v35
	v_exp_f32_e32 v36, v36
	v_exp_f32_e32 v37, v37
	v_exp_f32_e32 v38, v38
	v_exp_f32_e32 v39, v39
	v_exp_f32_e32 v40, v40
	v_exp_f32_e32 v41, v41
	v_exp_f32_e32 v42, v42
	v_exp_f32_e32 v43, v43
	v_exp_f32_e32 v44, v44
	v_exp_f32_e32 v45, v45
	v_exp_f32_e32 v46, v46
	v_exp_f32_e32 v47, v47
	v_add_f32_e32 v149, v48, v49
	v_add_f32_e32 v150, v56, v57
	v_add_f32_e32 v151, v32, v33
	v_add_f32_e32 v152, v40, v41
	v_add_f32_e32 v149, v149, v50
	v_add_f32_e32 v150, v150, v58
	v_add_f32_e32 v151, v151, v34
	v_add_f32_e32 v152, v152, v42
	v_add_f32_e32 v149, v149, v51
	v_add_f32_e32 v150, v150, v59
	v_add_f32_e32 v151, v151, v35
	v_add_f32_e32 v152, v152, v43
	v_add_f32_e32 v149, v149, v52
	v_add_f32_e32 v150, v150, v60
	v_add_f32_e32 v151, v151, v36
	v_add_f32_e32 v152, v152, v44
	v_add_f32_e32 v149, v149, v53
	v_add_f32_e32 v150, v150, v61
	v_add_f32_e32 v151, v151, v37
	v_add_f32_e32 v152, v152, v45
	v_add_f32_e32 v149, v149, v54
	v_add_f32_e32 v150, v150, v62
	v_add_f32_e32 v151, v151, v38
	v_add_f32_e32 v152, v152, v46
	v_add_f32_e32 v149, v149, v55
	v_add_f32_e32 v150, v150, v63
	v_add_f32_e32 v151, v151, v39
	v_add_f32_e32 v152, v152, v47
	v_cvt_pk_bf16_f32 v236, v48, v49
	v_cvt_pk_bf16_f32 v237, v50, v51
	v_cvt_pk_bf16_f32 v238, v52, v53
	v_cvt_pk_bf16_f32 v239, v54, v55
	v_cvt_pk_bf16_f32 v240, v56, v57
	v_cvt_pk_bf16_f32 v241, v58, v59
	v_cvt_pk_bf16_f32 v242, v60, v61
	v_cvt_pk_bf16_f32 v243, v62, v63
	v_cvt_pk_bf16_f32 v244, v32, v33
	v_cvt_pk_bf16_f32 v245, v34, v35
	v_cvt_pk_bf16_f32 v246, v36, v37
	v_cvt_pk_bf16_f32 v247, v38, v39
	v_cvt_pk_bf16_f32 v186, v40, v41
	v_cvt_pk_bf16_f32 v187, v42, v43
	v_cvt_pk_bf16_f32 v188, v44, v45
	v_cvt_pk_bf16_f32 v189, v46, v47
	v_add_f32_e32 v149, v149, v150
	v_add_f32_e32 v151, v151, v152
	v_add_f32_e32 v149, v149, v151
	v_add_f32_e32 v129, v129, v149
	s_waitcnt lgkmcnt(0)
	v_mfma_f32_32x32x16_bf16 v[16:31], v[192:195], v[236:239], v[16:31]
	v_mfma_f32_32x32x16_bf16 v[0:15], v[196:199], v[236:239], v[0:15]
	v_mfma_f32_32x32x16_bf16 v[16:31], v[200:203], v[240:243], v[16:31]
	v_mfma_f32_32x32x16_bf16 v[0:15], v[204:207], v[240:243], v[0:15]
	v_mfma_f32_32x32x16_bf16 v[16:31], v[208:211], v[244:247], v[16:31]
	v_mfma_f32_32x32x16_bf16 v[0:15], v[212:215], v[244:247], v[0:15]
	v_mfma_f32_32x32x16_bf16 v[16:31], v[216:219], v[186:189], v[16:31]
	v_mfma_f32_32x32x16_bf16 v[0:15], v[162:165], v[186:189], v[0:15]
	s_andn2_b64 vcc, exec, s[70:71]
	s_cbranch_vccnz .LBB0_1437
